# attention main loops: packed-f32 swaps folded into cvt operands and v_pk_add split into scalar adds; m_out CST/V loads hoisted
# speedup vs baseline: 1.0274x; 1.0046x over previous
.LBB0_820:
	ds_read_b128 v[66:69], v201
	ds_read_b128 v[70:73], v201 offset:32
	v_add_u32_e32 v209, 0x8800, v179
	v_exp_f32_e32 v163, v86
	v_exp_f32_e32 v162, v87
	s_waitcnt lgkmcnt(1)
	v_mfma_f32_32x32x16_bf16 v[50:65], v[66:69], v[114:117], v[34:49]
	v_exp_f32_e32 v82, v82
	v_exp_f32_e32 v83, v83
	v_exp_f32_e32 v84, v84
	v_exp_f32_e32 v85, v85
	v_exp_f32_e32 v87, v104
	v_exp_f32_e32 v86, v105
	s_waitcnt lgkmcnt(0)
	v_mfma_f32_32x32x16_bf16 v[50:65], v[70:73], v[118:121], v[50:65]
	ds_read_b128 v[66:69], v201 offset:64
	ds_read_b128 v[70:73], v201 offset:96
	v_exp_f32_e32 v175, v102
	v_exp_f32_e32 v174, v103
	v_cvt_pk_bf16_f32 v102, v82, v83
	v_cvt_pk_bf16_f32 v103, v84, v85
	v_cvt_pk_bf16_f32 v104, v163, v162
	v_exp_f32_e32 v177, v96
	s_waitcnt lgkmcnt(1)
	v_mfma_f32_32x32x16_bf16 v[50:65], v[66:69], v[122:125], v[50:65]
	ds_read_b128 v[66:69], v201 offset:128
	v_exp_f32_e32 v176, v97
	v_exp_f32_e32 v98, v98
	v_exp_f32_e32 v99, v99
	v_exp_f32_e32 v100, v100
	v_exp_f32_e32 v101, v101
	v_add_f32_e32 v181, v98, v82
	s_waitcnt lgkmcnt(1)
	v_mfma_f32_32x32x16_bf16 v[50:65], v[70:73], v[126:129], v[50:65]
	ds_read_b128 v[166:169], v201 offset:6656
	ds_read_b128 v[170:173], v201 offset:6688
	ds_read_b128 v[182:185], v201 offset:6720
	ds_read_b128 v[186:189], v201 offset:6752
	ds_read_b128 v[70:73], v201 offset:160
	ds_read_b128 v[210:213], v201 offset:6784
	ds_read_b128 v[214:217], v201 offset:6816
	v_add_f32_e32 v203, v99, v83
	v_add_f32_e32 v181, 0, v181
	v_add_f32_e32 v228, v100, v84
	v_add_f32_e32 v181, v203, v181
	v_add_f32_e32 v229, v101, v85
	s_waitcnt lgkmcnt(7)
	v_mfma_f32_32x32x16_bf16 v[50:65], v[66:69], v[130:133], v[50:65]
	v_add_f32_e64 v218, v174, v162
	v_add_f32_e64 v219, v175, v163
	s_add_i32 s12, s12, 2
	s_add_i32 s0, s90, 2
	s_add_i32 s1, s89, 2
	v_lshl_add_u64 v[150:151], v[150:151], 0, s[92:93]
	v_lshl_add_u64 v[152:153], v[152:153], 0, s[92:93]
	v_lshl_add_u64 v[160:161], v[160:161], 0, s[2:3]
	s_waitcnt lgkmcnt(2)
	v_mfma_f32_32x32x16_bf16 v[50:65], v[70:73], v[134:137], v[50:65]
	s_cmp_ge_u32 s12, s29
	v_mfma_f32_32x32x16_bf16 v[66:81], v[166:169], v[114:117], v[34:49]
	v_exp_f32_e32 v167, v88
	v_exp_f32_e32 v166, v89
	v_exp_f32_e32 v169, v90
	v_exp_f32_e32 v89, v106
	v_exp_f32_e32 v168, v91
	v_exp_f32_e32 v88, v107
	v_exp_f32_e32 v91, v108
	v_mfma_f32_32x32x16_bf16 v[66:81], v[170:173], v[118:121], v[66:81]
	v_exp_f32_e32 v90, v109
	ds_read2_b64 v[106:109], v209 offset0:64 offset1:66
	v_exp_f32_e32 v171, v92
	v_exp_f32_e32 v170, v93
	v_exp_f32_e32 v93, v110
	v_exp_f32_e32 v92, v111
	v_mfma_f32_32x32x16_bf16 v[66:81], v[182:185], v[122:125], v[66:81]
	v_cvt_pk_bf16_f32 v105, v167, v166
	v_exp_f32_e32 v173, v94
	v_exp_f32_e32 v172, v95
	v_exp_f32_e32 v95, v112
	v_exp_f32_e32 v94, v113
	ds_read2_b64 v[110:113], v209 offset0:68 offset1:70
	v_add_f32_e32 v220, v86, v166
	v_add_f32_e32 v221, v87, v167
	v_mfma_f32_32x32x16_bf16 v[66:81], v[186:189], v[126:129], v[66:81]
	v_add_f32_e32 v222, v88, v168
	v_add_f32_e32 v223, v89, v169
	v_add_f32_e32 v96, v90, v170
	v_add_f32_e32 v97, v91, v171
	v_add_f32_e32 v224, v92, v172
	v_add_f32_e32 v225, v93, v173
	v_add_f32_e32 v226, v94, v176
	v_add_f32_e32 v227, v95, v177
	s_waitcnt lgkmcnt(3)
	v_mfma_f32_32x32x16_bf16 v[66:81], v[210:213], v[130:133], v[66:81]
	v_add_u32_e32 v210, 0x9800, v179
	ds_read2_b64 v[182:185], v210 offset0:96 offset1:98
	s_nop 0
	v_cvt_pk_bf16_f32 v212, v89, v88
	s_waitcnt lgkmcnt(2)
	v_mfma_f32_32x32x16_bf16 v[2:17], v[106:109], v[102:105], v[2:17]
	v_cvt_pk_bf16_f32 v106, v169, v168
	v_cvt_pk_bf16_f32 v107, v171, v170
	v_cvt_pk_bf16_f32 v108, v173, v172
	v_cvt_pk_bf16_f32 v109, v177, v176
	s_waitcnt lgkmcnt(0)
	v_mfma_f32_32x32x16_bf16 v[18:33], v[182:185], v[102:105], v[18:33]
	ds_read2_b64 v[102:105], v210 offset0:100 offset1:102
	v_cvt_pk_bf16_f32 v184, v175, v174
	v_cvt_pk_bf16_f32 v185, v87, v86
	v_cvt_pk_bf16_f32 v182, v98, v99
	v_cvt_pk_bf16_f32 v183, v100, v101
	v_mfma_f32_32x32x16_bf16 v[2:17], v[110:113], v[106:109], v[2:17]
	ds_read2_b64 v[110:113], v209 offset0:72 offset1:74
	ds_read2_b64 v[186:189], v210 offset0:104 offset1:106
	s_waitcnt lgkmcnt(2)
	v_mfma_f32_32x32x16_bf16 v[18:33], v[102:105], v[106:109], v[18:33]
	s_waitcnt lgkmcnt(1)
	v_mfma_f32_32x32x16_bf16 v[2:17], v[110:113], v[182:185], v[2:17]
	v_add_f32_e32 v110, v228, v181
	v_add_f32_e32 v110, v229, v110
	v_add_f32_e32 v110, v219, v110
	v_add_f32_e32 v110, v218, v110
	v_add_f32_e32 v110, v221, v110
	v_add_f32_e32 v110, v220, v110
	v_add_f32_e32 v110, v223, v110
	s_waitcnt lgkmcnt(0)
	v_mfma_f32_32x32x16_bf16 v[18:33], v[186:189], v[182:185], v[18:33]
	v_add_f32_e32 v110, v222, v110
	v_add_f32_e32 v97, v97, v110
	v_add_f32_e32 v96, v96, v97
	v_add_f32_e32 v96, v225, v96
	v_add_f32_e32 v96, v224, v96
	v_add_f32_e32 v96, v227, v96
	v_add_f32_e32 v96, v226, v96
	v_mfma_f32_32x32x16_bf16 v[66:81], v[214:217], v[134:137], v[66:81]
	v_add_f32_e32 v203, v180, v96
	v_cvt_pk_bf16_f32 v213, v91, v90
	v_lshl_add_u64 v[96:97], v[156:157], 0, s[2:3]
	v_cvt_pk_bf16_f32 v214, v93, v92
	v_cvt_pk_bf16_f32 v215, v95, v94
	ds_read2_b64 v[102:105], v209 offset0:76 offset1:78
	ds_read2_b64 v[106:109], v210 offset0:108 offset1:110
	s_waitcnt lgkmcnt(1)
	v_mfma_f32_32x32x16_bf16 v[2:17], v[102:105], v[212:215], v[2:17]
	s_waitcnt lgkmcnt(0)
	v_mfma_f32_32x32x16_bf16 v[18:33], v[106:109], v[212:215], v[18:33]
	s_cbranch_scc0 .LBB0_800
	s_add_i32 s91, s29, 4
	s_mov_b64 s[8:9], -1
	s_cmp_lt_u32 s12, s91
	v_lshlrev_b32_e32 v158, 2, v178
	s_cbranch_scc1 .LBB0_823
	v_lshlrev_b32_e32 v0, 2, v178
	s_mov_b64 s[8:9], 0

.LBB0_875:
	ds_read_b128 v[2:5], v203
	ds_read_b128 v[6:9], v203 offset:32
	v_exp_f32_e32 v11, v100
	v_exp_f32_e32 v10, v101
	v_exp_f32_e32 v96, v96
	s_waitcnt lgkmcnt(1)
	v_mfma_f32_32x32x16_bf16 v[64:79], v[2:5], v[128:131], v[48:63]
	v_exp_f32_e32 v97, v97
	v_exp_f32_e32 v98, v98
	v_exp_f32_e32 v99, v99
	v_exp_f32_e32 v185, v126
	v_exp_f32_e32 v184, v127
	v_cvt_pk_bf16_f32 v100, v96, v97
	v_cvt_pk_bf16_f32 v101, v98, v99
	s_waitcnt lgkmcnt(0)
	v_mfma_f32_32x32x16_bf16 v[64:79], v[6:9], v[132:135], v[64:79]
	ds_read_b128 v[2:5], v203 offset:64
	ds_read_b128 v[6:9], v203 offset:96
	v_exp_f32_e32 v112, v112
	v_exp_f32_e32 v113, v113
	v_exp_f32_e32 v114, v114
	v_exp_f32_e32 v115, v115
	v_add_f32_e32 v189, v112, v96
	v_add_f32_e32 v208, v113, v97
	s_waitcnt lgkmcnt(1)
	v_mfma_f32_32x32x16_bf16 v[64:79], v[2:5], v[136:139], v[64:79]
	ds_read_b128 v[2:5], v203 offset:128
	v_add_f32_e32 v211, v114, v98
	v_add_f32_e32 v236, v115, v99
	s_add_i32 s76, s76, 2
	v_lshl_add_u64 v[178:179], v[178:179], 0, s[92:93]
	v_lshl_add_u64 v[180:181], v[180:181], 0, s[92:93]
	v_lshl_add_u64 v[182:183], v[182:183], 0, s[2:3]
	s_waitcnt lgkmcnt(1)
	v_mfma_f32_32x32x16_bf16 v[64:79], v[6:9], v[140:143], v[64:79]
	ds_read_b128 v[6:9], v203 offset:160
	s_cmp_ge_u32 s76, s15
	s_waitcnt lgkmcnt(1)
	v_mfma_f32_32x32x16_bf16 v[64:79], v[2:5], v[144:147], v[64:79]
	ds_read_b128 v[2:5], v203 offset:6656
	ds_read_b128 v[12:15], v203 offset:6688
	ds_read_b128 v[212:215], v203 offset:6720
	ds_read_b128 v[216:219], v203 offset:6752
	ds_read_b128 v[220:223], v203 offset:6784
	ds_read_b128 v[224:227], v203 offset:6816
	s_waitcnt lgkmcnt(5)
	v_mfma_f32_32x32x16_bf16 v[80:95], v[2:5], v[128:131], v[48:63]
	v_exp_f32_e32 v3, v116
	v_exp_f32_e32 v2, v117
	v_exp_f32_e32 v5, v118
	v_exp_f32_e32 v4, v119
	v_exp_f32_e32 v117, v104
	v_exp_f32_e32 v116, v105
	v_exp_f32_e32 v119, v106
	s_waitcnt lgkmcnt(4)
	v_mfma_f32_32x32x16_bf16 v[80:95], v[12:15], v[132:135], v[80:95]
	v_exp_f32_e32 v15, v102
	v_exp_f32_e32 v14, v103
	v_exp_f32_e32 v118, v107
	v_cvt_pk_bf16_f32 v102, v11, v10
	v_exp_f32_e32 v13, v124
	v_exp_f32_e32 v12, v125
	s_waitcnt lgkmcnt(3)
	v_mfma_f32_32x32x16_bf16 v[80:95], v[212:215], v[136:139], v[80:95]
	v_cvt_pk_bf16_f32 v124, v117, v116
	v_cvt_pk_bf16_f32 v125, v119, v118
	v_add_f32_e32 v190, v2, v10
	v_add_f32_e32 v191, v3, v11
	v_add_f32_e32 v228, v4, v14
	v_add_f32_e32 v229, v5, v15
	s_waitcnt lgkmcnt(2)
	v_mfma_f32_32x32x16_bf16 v[80:95], v[216:219], v[140:143], v[80:95]
	v_mfma_f32_32x32x16_bf16 v[64:79], v[6:9], v[148:151], v[64:79]
	v_exp_f32_e32 v7, v120
	v_exp_f32_e32 v6, v121
	v_exp_f32_e32 v121, v108
	v_exp_f32_e32 v120, v109
	v_exp_f32_e32 v9, v122
	v_exp_f32_e32 v8, v123
	s_waitcnt lgkmcnt(1)
	v_mfma_f32_32x32x16_bf16 v[80:95], v[220:223], v[144:147], v[80:95]
	v_add_u32_e32 v222, 0x8800, v0
	v_add_u32_e32 v0, 0x9800, v0
	v_exp_f32_e32 v123, v110
	v_exp_f32_e32 v122, v111
	ds_read2_b64 v[104:107], v222 offset0:64 offset1:66
	v_cvt_pk_bf16_f32 v103, v15, v14
	ds_read2_b64 v[108:111], v0 offset0:96 offset1:98
	s_waitcnt lgkmcnt(1)
	v_mfma_f32_32x32x16_bf16 v[32:47], v[104:107], v[100:103], v[32:47]
	ds_read2_b64 v[104:107], v222 offset0:68 offset1:70
	v_cvt_pk_bf16_f32 v126, v121, v120
	v_add_f32_e32 v230, v6, v116
	v_add_f32_e32 v231, v7, v117
	v_cvt_pk_bf16_f32 v216, v7, v6
	v_add_f32_e32 v232, v8, v118
	v_add_f32_e32 v233, v9, v119
	v_add_f32_e32 v234, v12, v120
	v_add_f32_e32 v235, v13, v121
	s_waitcnt lgkmcnt(1)
	v_mfma_f32_32x32x16_bf16 v[16:31], v[108:111], v[100:103], v[16:31]
	v_cvt_pk_bf16_f32 v127, v123, v122
	ds_read2_b64 v[100:103], v0 offset0:100 offset1:102
	v_cvt_pk_bf16_f32 v110, v3, v2
	v_cvt_pk_bf16_f32 v108, v112, v113
	v_cvt_pk_bf16_f32 v109, v114, v115
	s_waitcnt lgkmcnt(1)
	v_mfma_f32_32x32x16_bf16 v[32:47], v[104:107], v[124:127], v[32:47]
	v_add_f32_e32 v220, v184, v122
	v_add_f32_e32 v221, v185, v123
	v_cvt_pk_bf16_f32 v111, v5, v4
	ds_read2_b64 v[104:107], v222 offset0:72 offset1:74
	ds_read2_b64 v[212:215], v0 offset0:104 offset1:106
	s_waitcnt lgkmcnt(2)
	v_mfma_f32_32x32x16_bf16 v[16:31], v[100:103], v[124:127], v[16:31]
	s_nop 0
	v_cvt_pk_bf16_f32 v217, v9, v8
	s_nop 0
	v_cvt_pk_bf16_f32 v218, v13, v12
	s_waitcnt lgkmcnt(1)
	v_mfma_f32_32x32x16_bf16 v[32:47], v[104:107], v[108:111], v[32:47]
	v_cvt_pk_bf16_f32 v219, v185, v184
	ds_read2_b64 v[100:103], v222 offset0:76 offset1:78
	ds_read2_b64 v[104:107], v0 offset0:108 offset1:110
	v_add_f32_e32 v0, 0, v189
	v_add_f32_e32 v0, v208, v0
	v_add_f32_e32 v0, v211, v0
	v_add_f32_e32 v0, v236, v0
	s_waitcnt lgkmcnt(2)
	v_mfma_f32_32x32x16_bf16 v[16:31], v[212:215], v[108:111], v[16:31]
	v_add_f32_e32 v0, v191, v0
	v_add_f32_e32 v0, v190, v0
	v_add_f32_e32 v0, v229, v0
	v_add_f32_e32 v0, v228, v0
	v_add_f32_e32 v0, v231, v0
	v_add_f32_e32 v0, v230, v0
	v_add_f32_e32 v0, v233, v0
	v_mfma_f32_32x32x16_bf16 v[80:95], v[224:227], v[148:151], v[80:95]
	v_add_f32_e32 v0, v232, v0
	v_add_f32_e32 v0, v235, v0
	v_add_f32_e32 v0, v234, v0
	v_add_f32_e32 v0, v221, v0
	v_add_f32_e32 v0, v220, v0
	v_add_f32_e32 v208, v188, v0
	s_waitcnt lgkmcnt(1)
	v_mfma_f32_32x32x16_bf16 v[32:47], v[100:103], v[216:219], v[32:47]
	s_waitcnt lgkmcnt(0)
	v_mfma_f32_32x32x16_bf16 v[16:31], v[104:107], v[216:219], v[16:31]
	s_cbranch_scc1 .LBB0_894

; #define LAS __attribute__((address_space(3)))
; DI void phase_m_out(int wv, const ArgP a, LAS unsigned char* lds, int dry) {
;     ...
;         const int c = u >> 2, h = u & 3; const size_t t0 = (size_t)c * 64;
;         for (int e = tid; e < 1024; e += 512) { const int r = e >> 4, p = e & 15;
;             *(LAS u32x4*)(Qs + r * MC_QROW + p * 16) = *(const u32x4*)(QOK + (t0 + r) * 2048 + h * 128 + p * 8);
;             *(LAS u32x4*)(Ks + r * MC_QROW + p * 16) = *(const u32x4*)(QOK + (t0 + r) * 2048 + 1536 + h * 128 + p * 8); }
;     ...
;         { const bf16_t* cp = CST + ((size_t)(c * 4 + h) * 256 + 32 * w + r32) * 128 + 8 * hi;
; #pragma unroll
;           for (int ks = 0; ks < 8; ++ks) { const bf16x8 ca = *(const bf16x8*)(cp + 16 * ks);
;               const bf16x8 q0 = *(const LAS bf16x8*)(Qs + r32 * MC_QROW + (16 * ks + 8 * hi) * 2), q1 = *(const LAS bf16x8*)(Qs + (32 + r32) * MC_QROW + (16 * ks + 8 * hi) * 2);
;               acc0 = __builtin_amdgcn_mfma_f32_32x32x16_bf16(ca, q0, acc0, 0, 0, 0); acc1 = __builtin_amdgcn_mfma_f32_32x32x16_bf16(ca, q1, acc1, 0, 0, 0); } }
;         const float g0 = f_g[r32], g1 = f_g[32 + r32];
; #pragma unroll
;         for (int r = 0; r < 16; ++r) { acc0[r] *= g0; acc1[r] *= g1; }
;         { const bf16_t* vp = KVT + (size_t)(512 + h * 256 + 32 * w + r32) * S + t0 + 8 * hi;
; #pragma unroll
;           for (int ks = 0; ks < 4; ++ks) { const bf16x8 va = *(const bf16x8*)(vp + 16 * ks);
.LBB0_1606:
	s_ashr_i32 s48, s66, 2
	s_ashr_i32 s49, s48, 31
	s_and_b32 s76, s66, 3
	s_lshl_b64 s[68:69], s[48:49], 6
	s_ashr_i32 s99, s66, 31
	s_mov_b32 s98, s66
	s_lshl_b64 s[98:99], s[98:99], 16
	v_lshl_add_u64 v[188:189], v[50:51], 0, s[98:99]
	global_load_dwordx4 v[140:143], v[188:189], off
	global_load_dwordx4 v[144:147], v[188:189], off offset:32
	global_load_dwordx4 v[148:151], v[188:189], off offset:64
	global_load_dwordx4 v[152:155], v[188:189], off offset:96
	global_load_dwordx4 v[156:159], v[188:189], off offset:128
	global_load_dwordx4 v[160:163], v[188:189], off offset:160
	global_load_dwordx4 v[164:167], v[188:189], off offset:192
	global_load_dwordx4 v[168:171], v[188:189], off offset:224
	s_lshl_b32 s98, s76, 8
	v_add_u32_e32 v190, s98, v69
	v_ashrrev_i32_e32 v191, 31, v190
	v_lshlrev_b64 v[190:191], 15, v[190:191]
	v_lshl_add_u64 v[190:191], s[50:51], 0, v[190:191]
	v_lshl_add_u64 v[190:191], s[68:69], 1, v[190:191]
	v_lshl_add_u64 v[190:191], v[190:191], 0, v[36:37]
	global_load_dwordx4 v[172:175], v[190:191], off
	global_load_dwordx4 v[176:179], v[190:191], off offset:32
	global_load_dwordx4 v[180:183], v[190:191], off offset:64
	global_load_dwordx4 v[184:187], v[190:191], off offset:96
	s_and_saveexec_b64 s[48:49], s[4:5]
	s_cbranch_execz .LBB0_1609
	s_lshl_b32 s0, s76, 8
	v_lshl_add_u64 v[0:1], v[52:53], 0, s[0:1]
	s_mov_b64 s[70:71], 0
	v_mov_b32_e32 v2, v32

; #define LAS __attribute__((address_space(3)))
; DI float fexp(float x) { return __builtin_amdgcn_exp2f(x * LOG2E); }
; DI void phase_m_out(int wv, const ArgP a, LAS unsigned char* lds, int dry) {
;     ...
;         f32x16 acc0 = {}, acc1 = {};
;         { const bf16_t* cp = CST + ((size_t)(c * 4 + h) * 256 + 32 * w + r32) * 128 + 8 * hi;
; #pragma unroll
;           for (int ks = 0; ks < 8; ++ks) { const bf16x8 ca = *(const bf16x8*)(cp + 16 * ks);
;               const bf16x8 q0 = *(const LAS bf16x8*)(Qs + r32 * MC_QROW + (16 * ks + 8 * hi) * 2), q1 = *(const LAS bf16x8*)(Qs + (32 + r32) * MC_QROW + (16 * ks + 8 * hi) * 2);
;               acc0 = __builtin_amdgcn_mfma_f32_32x32x16_bf16(ca, q0, acc0, 0, 0, 0); acc1 = __builtin_amdgcn_mfma_f32_32x32x16_bf16(ca, q1, acc1, 0, 0, 0); } }
;         const float g0 = f_g[r32], g1 = f_g[32 + r32];
; #pragma unroll
;         for (int r = 0; r < 16; ++r) { acc0[r] *= g0; acc1[r] *= g1; }
;         { const bf16_t* vp = KVT + (size_t)(512 + h * 256 + 32 * w + r32) * S + t0 + 8 * hi;
; #pragma unroll
;           for (int ks = 0; ks < 4; ++ks) { const bf16x8 va = *(const bf16x8*)(vp + 16 * ks);
;               const bf16x8 s0 = *(const LAS bf16x8*)(Sc + r32 * MC_SROW + (16 * ks + 8 * hi) * 2), s1 = *(const LAS bf16x8*)(Sc + (32 + r32) * MC_SROW + (16 * ks + 8 * hi) * 2);
;               acc0 = __builtin_amdgcn_mfma_f32_32x32x16_bf16(va, s0, acc0, 0, 0, 0); acc1 = __builtin_amdgcn_mfma_f32_32x32x16_bf16(va, s1, acc1, 0, 0, 0); } }
;         float inv[2];
; #pragma unroll
;         for (int tb = 0; tb < 2; ++tb) { const int tl = 32 * tb + r32;
;             const float den = f_g[tl] * f_qn[tl] + f_ps[tl] + f_ps[64 + tl] + f_ps[128 + tl] + f_ps[192 + tl];
;             inv[tb] = 1.f / fmaxf(fabsf(den), fexp(-f_m[tl])); }
.LBB0_1647:
	s_ashr_i32 s67, s66, 31
	s_lshl_b64 s[48:49], s[66:67], 16
	v_lshl_add_u64 v[96:97], v[50:51], 0, s[48:49]
	s_waitcnt lgkmcnt(0)
	s_barrier
	s_waitcnt vmcnt(0)
	v_mov_b32_e32 v0, v140
	v_mov_b32_e32 v1, v141
	v_mov_b32_e32 v2, v142
	v_mov_b32_e32 v3, v143
	v_mov_b32_e32 v60, v144
	v_mov_b32_e32 v61, v145
	v_mov_b32_e32 v62, v146
	v_mov_b32_e32 v63, v147
	v_add_u32_e32 v57, v59, v40
	ds_read_b128 v[4:7], v57
	ds_read_b128 v[64:67], v57 offset:32
	s_lshl_b32 s67, s76, 8
	v_add_u32_e32 v128, 0xac00, v68
	v_add_u32_e32 v136, 0xac00, v35
	v_add_u32_e32 v75, 0xb400, v35
	s_waitcnt vmcnt(1) lgkmcnt(1)
	v_mfma_f32_32x32x16_bf16 v[16:31], v[0:3], v[4:7], 0
	ds_read_b128 v[4:7], v57 offset:8704
	ds_read_b128 v[76:79], v57 offset:8736
	v_mov_b32_e32 v80, v148
	v_mov_b32_e32 v81, v149
	v_mov_b32_e32 v82, v150
	v_mov_b32_e32 v83, v151
	s_waitcnt vmcnt(1) lgkmcnt(2)
	v_mfma_f32_32x32x16_bf16 v[16:31], v[60:63], v[64:67], v[16:31]
	v_mov_b32_e32 v64, v152
	v_mov_b32_e32 v65, v153
	v_mov_b32_e32 v66, v154
	v_mov_b32_e32 v67, v155
	s_waitcnt lgkmcnt(1)
	v_mfma_f32_32x32x16_bf16 v[0:15], v[0:3], v[4:7], 0
	s_waitcnt lgkmcnt(0)
	v_mfma_f32_32x32x16_bf16 v[0:15], v[60:63], v[76:79], v[0:15]
	v_mov_b32_e32 v60, v156
	v_mov_b32_e32 v61, v157
	v_mov_b32_e32 v62, v158
	v_mov_b32_e32 v63, v159
	ds_read_b128 v[76:79], v57 offset:64
	ds_read_b128 v[84:87], v57 offset:96
	s_waitcnt vmcnt(2) lgkmcnt(1)
	v_mfma_f32_32x32x16_bf16 v[16:31], v[80:83], v[76:79], v[16:31]
	v_mov_b32_e32 v76, v160
	v_mov_b32_e32 v77, v161
	v_mov_b32_e32 v78, v162
	v_mov_b32_e32 v79, v163
	ds_read_b128 v[88:91], v57 offset:8768
	ds_read_b128 v[92:95], v57 offset:8800
	s_waitcnt lgkmcnt(1)
	v_mfma_f32_32x32x16_bf16 v[0:15], v[80:83], v[88:91], v[0:15]
	v_mov_b32_e32 v80, v164
	v_mov_b32_e32 v81, v165
	v_mov_b32_e32 v82, v166
	v_mov_b32_e32 v83, v167
	s_waitcnt vmcnt(3)
	v_mfma_f32_32x32x16_bf16 v[16:31], v[64:67], v[84:87], v[16:31]
	v_mov_b32_e32 v84, v168
	v_mov_b32_e32 v85, v169
	v_mov_b32_e32 v86, v170
	v_mov_b32_e32 v87, v171
	s_waitcnt lgkmcnt(0)
	v_mfma_f32_32x32x16_bf16 v[0:15], v[64:67], v[92:95], v[0:15]
	v_add_u32_e32 v92, s67, v69
	v_ashrrev_i32_e32 v93, 31, v92
	ds_read_b128 v[64:67], v57 offset:128
	ds_read_b128 v[88:91], v57 offset:160
	v_lshlrev_b64 v[92:93], 15, v[92:93]
	v_lshl_add_u64 v[92:93], s[50:51], 0, v[92:93]
	v_lshl_add_u64 v[92:93], s[68:69], 1, v[92:93]
	v_lshl_add_u64 v[100:101], v[92:93], 0, v[36:37]
	s_waitcnt vmcnt(3) lgkmcnt(1)
	v_mfma_f32_32x32x16_bf16 v[16:31], v[60:63], v[64:67], v[16:31]
	v_mov_b32_e32 v64, v172
	v_mov_b32_e32 v65, v173
	v_mov_b32_e32 v66, v174
	v_mov_b32_e32 v67, v175
	ds_read_b128 v[92:95], v57 offset:8832
	ds_read_b128 v[96:99], v57 offset:8864
	s_waitcnt lgkmcnt(1)
	v_mfma_f32_32x32x16_bf16 v[0:15], v[60:63], v[92:95], v[0:15]
	v_mov_b32_e32 v60, v176
	v_mov_b32_e32 v61, v177
	v_mov_b32_e32 v62, v178
	v_mov_b32_e32 v63, v179
	s_waitcnt vmcnt(4)
	v_mfma_f32_32x32x16_bf16 v[16:31], v[76:79], v[88:91], v[16:31]
	v_mov_b32_e32 v88, v180
	v_mov_b32_e32 v89, v181
	v_mov_b32_e32 v90, v182
	v_mov_b32_e32 v91, v183
	s_waitcnt lgkmcnt(0)
	v_mfma_f32_32x32x16_bf16 v[0:15], v[76:79], v[96:99], v[0:15]
	v_mov_b32_e32 v76, v184
	v_mov_b32_e32 v77, v185
	v_mov_b32_e32 v78, v186
	v_mov_b32_e32 v79, v187
	ds_read_b128 v[92:95], v57 offset:192
	ds_read_b128 v[96:99], v57 offset:224
	s_waitcnt vmcnt(5) lgkmcnt(1)
	v_mfma_f32_32x32x16_bf16 v[16:31], v[80:83], v[92:95], v[16:31]
	ds_read_b128 v[92:95], v57 offset:8896
	ds_read_b128 v[100:103], v73 offset:34816
	ds_read_b128 v[104:107], v73 offset:34848
	ds_read_b128 v[108:111], v73 offset:39424
	ds_read_b128 v[112:115], v73 offset:39456
	ds_read_b128 v[116:119], v57 offset:8928
	v_add_u32_e32 v57, 0xb000, v35
	s_waitcnt lgkmcnt(5)
	v_mfma_f32_32x32x16_bf16 v[0:15], v[80:83], v[92:95], v[0:15]
	ds_read_b128 v[80:83], v73 offset:34880
	ds_read_b128 v[92:95], v73 offset:34912
	ds_read_b128 v[120:123], v73 offset:39488
	ds_read_b128 v[124:127], v73 offset:39520
	ds_read2_b32 v[128:129], v128 offset0:192 offset1:224
	s_waitcnt lgkmcnt(0)
	v_mov_b32_e32 v138, v129
	s_waitcnt vmcnt(4)
	v_mfma_f32_32x32x16_bf16 v[16:31], v[84:87], v[96:99], v[16:31]
	ds_read2_b32 v[96:97], v57 offset1:32
	ds_read2_b32 v[98:99], v57 offset0:64 offset1:96
	ds_read2_b32 v[130:131], v57 offset0:128 offset1:160
	ds_read2_b32 v[132:133], v57 offset0:192 offset1:224
	ds_read2_b32 v[134:135], v75 offset1:32
	ds_read2_b32 v[136:137], v136 offset0:128 offset1:160
	s_waitcnt lgkmcnt(4)
	v_fma_f32 v57, v128, v96, v98
	s_waitcnt lgkmcnt(3)
	v_add_f32_e32 v57, v57, v130
	v_fmac_f32_e32 v99, v129, v97
	s_waitcnt lgkmcnt(2)
	v_add_f32_e32 v57, v57, v132
	s_waitcnt lgkmcnt(1)
; #define LAS __attribute__((address_space(3)))
; DI float fexp(float x) { return __builtin_amdgcn_exp2f(x * LOG2E); }
; DI void phase_m_out(int wv, const ArgP a, LAS unsigned char* lds, int dry) {
;     ...
;         const float g0 = f_g[r32], g1 = f_g[32 + r32];
; #pragma unroll
;         for (int r = 0; r < 16; ++r) { acc0[r] *= g0; acc1[r] *= g1; }
;         { const bf16_t* vp = KVT + (size_t)(512 + h * 256 + 32 * w + r32) * S + t0 + 8 * hi;
; #pragma unroll
;           for (int ks = 0; ks < 4; ++ks) { const bf16x8 va = *(const bf16x8*)(vp + 16 * ks);
;               const bf16x8 s0 = *(const LAS bf16x8*)(Sc + r32 * MC_SROW + (16 * ks + 8 * hi) * 2), s1 = *(const LAS bf16x8*)(Sc + (32 + r32) * MC_SROW + (16 * ks + 8 * hi) * 2);
;               acc0 = __builtin_amdgcn_mfma_f32_32x32x16_bf16(va, s0, acc0, 0, 0, 0); acc1 = __builtin_amdgcn_mfma_f32_32x32x16_bf16(va, s1, acc1, 0, 0, 0); } }
;         float inv[2];
; #pragma unroll
;         for (int tb = 0; tb < 2; ++tb) { const int tl = 32 * tb + r32;
;             const float den = f_g[tl] * f_qn[tl] + f_ps[tl] + f_ps[64 + tl] + f_ps[128 + tl] + f_ps[192 + tl];
;             inv[tb] = 1.f / fmaxf(fabsf(den), fexp(-f_m[tl])); }
;         float ss0 = 0.f, ss1 = 0.f;
; #pragma unroll
;         for (int r = 0; r < 16; ++r) { acc0[r] *= inv[0]; acc1[r] *= inv[1]; ss0 += acc0[r] * acc0[r]; ss1 += acc1[r] * acc1[r]; }
;         ss0 += __shfl_xor(ss0, 32); ss1 += __shfl_xor(ss1, 32);
;         if (hi == 0) { f_part[w * 64 + r32] = ss0; f_part[w * 64 + 32 + r32] = ss1; }
	v_add_f32_e32 v57, v57, v134
	v_pk_mul_f32 v[30:31], v[30:31], v[128:129] op_sel_hi:[1,0]
	v_mfma_f32_32x32x16_bf16 v[0:15], v[84:87], v[116:119], v[0:15]
	v_mul_f32_e64 v28, v28, v128
	v_mul_f32_e64 v29, v29, v128
	v_mul_f32_e64 v26, v26, v128
	v_mul_f32_e64 v27, v27, v128
	v_mul_f32_e64 v24, v24, v128
	v_mul_f32_e64 v25, v25, v128
	v_pk_mul_f32 v[22:23], v[22:23], v[128:129] op_sel_hi:[1,0]
	v_pk_mul_f32 v[20:21], v[20:21], v[128:129] op_sel_hi:[1,0]
	v_pk_mul_f32 v[18:19], v[18:19], v[128:129] op_sel_hi:[1,0]
	v_pk_mul_f32 v[16:17], v[16:17], v[128:129] op_sel_hi:[1,0]
	s_nop 1
	v_pk_mul_f32 v[14:15], v[14:15], v[138:139] op_sel_hi:[1,0]
	v_pk_mul_f32 v[12:13], v[12:13], v[138:139] op_sel_hi:[1,0]
	v_pk_mul_f32 v[10:11], v[10:11], v[138:139] op_sel_hi:[1,0]
	v_pk_mul_f32 v[8:9], v[8:9], v[138:139] op_sel_hi:[1,0]
	v_pk_mul_f32 v[6:7], v[6:7], v[138:139] op_sel_hi:[1,0]
	v_pk_mul_f32 v[4:5], v[4:5], v[138:139] op_sel_hi:[1,0]
	v_pk_mul_f32 v[2:3], v[2:3], v[138:139] op_sel_hi:[1,0]
	v_pk_mul_f32 v[0:1], v[0:1], v[138:139] op_sel_hi:[1,0]
	s_waitcnt vmcnt(3)
	v_mfma_f32_32x32x16_bf16 v[16:31], v[64:67], v[100:103], v[16:31]
	v_mfma_f32_32x32x16_bf16 v[0:15], v[64:67], v[108:111], v[0:15]
	s_waitcnt lgkmcnt(0)
	v_mul_f32_e32 v64, 0xbfb8aa3b, v136
	v_exp_f32_e32 v64, v64
	v_mul_f32_e32 v65, 0xbfb8aa3b, v137
	v_exp_f32_e32 v65, v65
	v_add_f32_e32 v66, v99, v131
	v_add_f32_e32 v66, v66, v133
	v_max_f32_e64 v57, |v57|, v64
	s_waitcnt vmcnt(2)
	v_mfma_f32_32x32x16_bf16 v[16:31], v[60:63], v[104:107], v[16:31]
	v_add_f32_e32 v66, v66, v135
	v_max_f32_e64 v64, |v66|, v65
	v_mfma_f32_32x32x16_bf16 v[0:15], v[60:63], v[112:115], v[0:15]
	v_div_scale_f32 v60, s[48:49], v57, v57, 1.0
	v_rcp_f32_e32 v63, v60
	v_div_scale_f32 v62, s[48:49], v64, v64, 1.0
	v_rcp_f32_e32 v65, v62
	v_fma_f32 v67, -v60, v63, 1.0
	s_waitcnt vmcnt(1)
	v_mfma_f32_32x32x16_bf16 v[16:31], v[88:91], v[80:83], v[16:31]
	v_div_scale_f32 v61, vcc, 1.0, v57, 1.0
	v_fmac_f32_e32 v63, v67, v63
	v_fma_f32 v80, -v62, v65, 1.0
	v_mul_f32_e32 v67, v61, v63
	v_div_scale_f32 v66, s[48:49], 1.0, v64, 1.0
	v_mfma_f32_32x32x16_bf16 v[0:15], v[88:91], v[120:123], v[0:15]
	v_fmac_f32_e32 v65, v80, v65
	v_fma_f32 v80, -v60, v67, v61
	v_mul_f32_e32 v81, v66, v65
	v_fmac_f32_e32 v67, v80, v63
	v_fma_f32 v82, -v62, v81, v66
	v_fma_f32 v60, -v60, v67, v61
	v_div_fmas_f32 v60, v60, v63, v67
	s_waitcnt vmcnt(0)
	v_mfma_f32_32x32x16_bf16 v[16:31], v[76:79], v[92:95], v[16:31]
	v_fmac_f32_e32 v81, v82, v65
	v_div_fixup_f32 v80, v60, v57, 1.0
	v_fma_f32 v57, -v62, v81, v66
	s_mov_b64 vcc, s[48:49]
	v_div_fmas_f32 v57, v57, v65, v81
	v_div_fixup_f32 v82, v57, v64, 1.0
	s_nop 5
	v_pk_mul_f32 v[64:65], v[16:17], v[80:81] op_sel_hi:[1,0]
	v_mfma_f32_32x32x16_bf16 v[0:15], v[76:79], v[124:127], v[0:15]
	v_mul_f32_e64 v84, v64, v64
	v_mul_f32_e64 v85, v65, v65
	v_mul_f32_e64 v66, v18, v80
	v_mul_f32_e64 v67, v19, v80
	v_add_f32_e32 v57, v84, v85
	v_pk_mul_f32 v[78:79], v[66:67], v[66:67]
	v_pk_mul_f32 v[62:63], v[20:21], v[80:81] op_sel_hi:[1,0]
	v_add_f32_e32 v57, v78, v57
	v_pk_mul_f32 v[88:89], v[62:63], v[62:63]
	s_nop 2
	v_pk_mul_f32 v[16:17], v[82:83], v[0:1] op_sel_hi:[0,1]
	v_pk_mul_f32 v[76:77], v[16:17], v[16:17]
	v_pk_mul_f32 v[18:19], v[82:83], v[2:3] op_sel_hi:[0,1]
	v_pk_mul_f32 v[86:87], v[18:19], v[18:19]
	v_add_f32_e32 v76, v76, v77
	v_pk_mul_f32 v[20:21], v[82:83], v[4:5] op_sel_hi:[0,1]
	v_add_f32_e32 v76, v86, v76
	v_pk_mul_f32 v[90:91], v[20:21], v[20:21]
	v_add_f32_e32 v57, v79, v57
	v_add_f32_e32 v76, v87, v76
	v_pk_mul_f32 v[60:61], v[22:23], v[80:81] op_sel_hi:[1,0]
	v_pk_mul_f32 v[22:23], v[82:83], v[6:7] op_sel_hi:[0,1]
	v_add_f32_e32 v57, v88, v57
	v_add_f32_e32 v76, v90, v76
	v_pk_mul_f32 v[92:93], v[60:61], v[60:61]
	v_pk_mul_f32 v[94:95], v[22:23], v[22:23]
	v_add_f32_e32 v57, v89, v57
	v_add_f32_e32 v76, v91, v76
	v_pk_mul_f32 v[24:25], v[24:25], v[80:81] op_sel_hi:[1,0]
	v_pk_mul_f32 v[0:1], v[82:83], v[8:9] op_sel_hi:[0,1]
	v_add_f32_e32 v57, v92, v57
	v_add_f32_e32 v76, v94, v76
	v_pk_mul_f32 v[96:97], v[24:25], v[24:25]
	v_pk_mul_f32 v[8:9], v[0:1], v[0:1]
	v_add_f32_e32 v57, v93, v57
	v_add_f32_e32 v76, v95, v76
	v_pk_mul_f32 v[26:27], v[26:27], v[80:81] op_sel_hi:[1,0]
	v_pk_mul_f32 v[2:3], v[82:83], v[10:11] op_sel_hi:[0,1]
	v_add_f32_e32 v57, v96, v57
	v_add_f32_e32 v8, v8, v76
	v_pk_mul_f32 v[98:99], v[26:27], v[26:27]
	v_pk_mul_f32 v[100:101], v[2:3], v[2:3]
	v_add_f32_e32 v57, v97, v57
	v_add_f32_e32 v8, v9, v8
	v_pk_mul_f32 v[10:11], v[28:29], v[80:81] op_sel_hi:[1,0]
	v_pk_mul_f32 v[4:5], v[82:83], v[12:13] op_sel_hi:[0,1]
	v_add_f32_e32 v9, v98, v57
	v_add_f32_e32 v57, v100, v8
	v_pk_mul_f32 v[28:29], v[10:11], v[10:11]
	v_pk_mul_f32 v[102:103], v[4:5], v[4:5]
	v_add_f32_e32 v8, v99, v9
	v_add_f32_e32 v9, v101, v57
	v_pk_mul_f32 v[12:13], v[30:31], v[80:81] op_sel_hi:[1,0]
	v_pk_mul_f32 v[6:7], v[82:83], v[14:15] op_sel_hi:[0,1]
	v_add_f32_e32 v8, v28, v8
	v_add_f32_e32 v9, v102, v9
	v_pk_mul_f32 v[30:31], v[12:13], v[12:13]
	v_pk_mul_f32 v[14:15], v[6:7], v[6:7]
	v_add_f32_e32 v8, v29, v8
	v_add_f32_e32 v9, v103, v9
	v_add_f32_e32 v8, v30, v8
	v_add_f32_e32 v9, v14, v9
	v_add_f32_e32 v8, v31, v8
	v_add_f32_e32 v9, v15, v9
	ds_bpermute_b32 v14, v195, v8
	ds_bpermute_b32 v15, v195, v9
	s_and_saveexec_b64 s[48:49], s[12:13]
	s_cbranch_execz .LBB0_1605
	s_waitcnt lgkmcnt(0)
	v_add_f32_e32 v9, v9, v15
	v_add_f32_e32 v8, v8, v14
	ds_write2_b32 v74, v8, v9 offset0:192 offset1:224
	s_branch .LBB0_1605

; #define LAS __attribute__((address_space(3)))
; __global__ void __launch_bounds__(512, 2) fwd_kernel(Args a_unused) {
;     extern __shared__ __attribute__((aligned(16))) unsigned char shm[];
;     LAS unsigned char* lds = (LAS unsigned char*)shm;
;     const int wv = __builtin_amdgcn_readfirstlane(threadIdx.x >> 6);
	.amdhsa_kernel _Z10fwd_kernel4Args
		.amdhsa_group_segment_fixed_size 0
		.amdhsa_private_segment_fixed_size 0
		.amdhsa_kernarg_size 504
		.amdhsa_user_sgpr_count 2
		.amdhsa_user_sgpr_dispatch_ptr 0
		.amdhsa_user_sgpr_queue_ptr 0
		.amdhsa_user_sgpr_kernarg_segment_ptr 1
		.amdhsa_user_sgpr_dispatch_id 0
		.amdhsa_user_sgpr_kernarg_preload_length 0
		.amdhsa_user_sgpr_kernarg_preload_offset 0
		.amdhsa_user_sgpr_private_segment_size 0
		.amdhsa_uses_dynamic_stack 0
		.amdhsa_enable_private_segment 0
		.amdhsa_system_sgpr_workgroup_id_x 1
		.amdhsa_system_sgpr_workgroup_id_y 0
		.amdhsa_system_sgpr_workgroup_id_z 0
		.amdhsa_system_sgpr_workgroup_info 0
		.amdhsa_system_vgpr_workitem_id 2
		.amdhsa_next_free_vgpr 256
		.amdhsa_next_free_sgpr 100
		.amdhsa_accum_offset 256
		.amdhsa_reserve_vcc 1
		.amdhsa_float_round_mode_32 0
		.amdhsa_float_round_mode_16_64 0
		.amdhsa_float_denorm_mode_32 3
		.amdhsa_float_denorm_mode_16_64 3
		.amdhsa_dx10_clamp 1
		.amdhsa_ieee_mode 1
		.amdhsa_fp16_overflow 0
		.amdhsa_tg_split 0
		.amdhsa_exception_fp_ieee_invalid_op 0
		.amdhsa_exception_fp_denorm_src 0
		.amdhsa_exception_fp_ieee_div_zero 0
		.amdhsa_exception_fp_ieee_overflow 0
		.amdhsa_exception_fp_ieee_underflow 0
		.amdhsa_exception_fp_ieee_inexact 0
		.amdhsa_exception_int_div_zero 0
	.end_amdhsa_kernel

; __global__ void __launch_bounds__(512, 2) fwd_kernel(Args a_unused) {
amdhsa.kernels:
  - .agpr_count:     0
    .args:
      - .offset:         0
        .size:           248
        .value_kind:     by_value
      - .offset:         248
        .size:           4
        .value_kind:     hidden_block_count_x
      - .offset:         252
        .size:           4
        .value_kind:     hidden_block_count_y
      - .offset:         256
        .size:           4
        .value_kind:     hidden_block_count_z
      - .offset:         260
        .size:           2
        .value_kind:     hidden_group_size_x
      - .offset:         262
        .size:           2
        .value_kind:     hidden_group_size_y
      - .offset:         264
        .size:           2
        .value_kind:     hidden_group_size_z
      - .offset:         266
        .size:           2
        .value_kind:     hidden_remainder_x
      - .offset:         268
        .size:           2
        .value_kind:     hidden_remainder_y
      - .offset:         270
        .size:           2
        .value_kind:     hidden_remainder_z
      - .offset:         288
        .size:           8
        .value_kind:     hidden_global_offset_x
      - .offset:         296
        .size:           8
        .value_kind:     hidden_global_offset_y
      - .offset:         304
        .size:           8
        .value_kind:     hidden_global_offset_z
      - .offset:         312
        .size:           2
        .value_kind:     hidden_grid_dims
      - .offset:         336
        .size:           8
        .value_kind:     hidden_multigrid_sync_arg
      - .offset:         368
        .size:           4
        .value_kind:     hidden_dynamic_lds_size
    .group_segment_fixed_size: 0
    .kernarg_segment_align: 8
    .kernarg_segment_size: 504
    .language:       OpenCL C
    .language_version:
      - 2
      - 0
    .max_flat_workgroup_size: 512
    .name:           _Z10fwd_kernel4Args
    .private_segment_fixed_size: 0
    .sgpr_count:     106
    .sgpr_spill_count: 24
    .symbol:         _Z10fwd_kernel4Args.kd
    .uniform_work_group_size: 1
    .uses_dynamic_stack: false
    .vgpr_count:     256
    .vgpr_spill_count: 0
    .wavefront_size: 64
